# FFN SwiGLU epilogue as 8 interleaved chains; MFMA K-step pairs adjacent per accumulator; post-MMA barrier 4 MFMAs early with prio raise, all three GEMM loops
# speedup vs baseline: 1.0092x; 1.0059x over previous
.LBB0_143:
	s_add_u32 s26, s16, 0xfffc0080
	s_addc_u32 s27, s17, -1
	s_add_i32 s34, 0, 0x10000
	s_cmp_eq_u32 s37, 12
	s_cselect_b32 s31, s9, s27
	s_cselect_b32 s30, s25, s26
	v_add_u32_e32 v138, s34, v141
	s_cselect_b32 s27, s7, s36
	s_cselect_b32 s26, s28, s29
	s_add_i32 s40, 0, 0x14000
	ds_read_b128 v[144:147], v138
	ds_read_b128 v[148:151], v138 offset:1024
	ds_read_b128 v[152:155], v138 offset:2048
	ds_read_b128 v[156:159], v138 offset:3072
	v_add_u32_e32 v138, s40, v141
	ds_read_b128 v[160:163], v138
	ds_read_b128 v[164:167], v138 offset:1024
	ds_read_b128 v[168:171], v138 offset:2048
	ds_read_b128 v[172:175], v138 offset:3072
	v_lshl_add_u64 v[138:139], s[16:17], 0, v[132:133]
	s_add_i32 m0, s53, 0xc000
	ds_read_b128 v[176:179], v143
	ds_read_b128 v[180:183], v143 offset:1024
	ds_read_b128 v[184:187], v143 offset:2048
	ds_read_b128 v[188:191], v143 offset:3072
	ds_read_b128 v[192:195], v143 offset:4096
	ds_read_b128 v[196:199], v143 offset:5120
	ds_read_b128 v[200:203], v143 offset:6144
	ds_read_b128 v[204:207], v143 offset:7168
	global_load_lds_dwordx4 v[138:139], off
	v_lshl_add_u64 v[138:139], s[16:17], 0, v[134:135]
	s_add_i32 m0, s53, 0xe000
	s_nop 0
	global_load_lds_dwordx4 v[138:139], off
	s_waitcnt vmcnt(8)
	s_waitcnt lgkmcnt(0)
	s_barrier
	s_setprio 1
	s_waitcnt lgkmcnt(0)
	v_mfma_f32_16x16x32_bf16 v[126:129], v[144:147], v[176:179], v[126:129]
	v_mfma_f32_16x16x32_bf16 v[126:129], v[148:151], v[180:183], v[126:129]
	v_mfma_f32_16x16x32_bf16 v[118:121], v[152:155], v[176:179], v[118:121]
	v_mfma_f32_16x16x32_bf16 v[118:121], v[156:159], v[180:183], v[118:121]
	v_mfma_f32_16x16x32_bf16 v[110:113], v[144:147], v[184:187], v[110:113]
	v_mfma_f32_16x16x32_bf16 v[110:113], v[148:151], v[188:191], v[110:113]
	v_mfma_f32_16x16x32_bf16 v[102:105], v[152:155], v[184:187], v[102:105]
	v_mfma_f32_16x16x32_bf16 v[102:105], v[156:159], v[188:191], v[102:105]
	v_mfma_f32_16x16x32_bf16 v[94:97], v[144:147], v[192:195], v[94:97]
	v_mfma_f32_16x16x32_bf16 v[94:97], v[148:151], v[196:199], v[94:97]
	v_mfma_f32_16x16x32_bf16 v[86:89], v[152:155], v[192:195], v[86:89]
	v_mfma_f32_16x16x32_bf16 v[86:89], v[156:159], v[196:199], v[86:89]
	v_mfma_f32_16x16x32_bf16 v[78:81], v[144:147], v[200:203], v[78:81]
	v_mfma_f32_16x16x32_bf16 v[78:81], v[148:151], v[204:207], v[78:81]
	v_mfma_f32_16x16x32_bf16 v[70:73], v[152:155], v[200:203], v[70:73]
	v_mfma_f32_16x16x32_bf16 v[70:73], v[156:159], v[204:207], v[70:73]
	s_setprio 0
	s_setprio 1
	v_mfma_f32_16x16x32_bf16 v[122:125], v[160:163], v[176:179], v[122:125]
	v_mfma_f32_16x16x32_bf16 v[122:125], v[164:167], v[180:183], v[122:125]
	v_mfma_f32_16x16x32_bf16 v[114:117], v[168:171], v[176:179], v[114:117]
	v_mfma_f32_16x16x32_bf16 v[114:117], v[172:175], v[180:183], v[114:117]
	v_mfma_f32_16x16x32_bf16 v[106:109], v[160:163], v[184:187], v[106:109]
	v_mfma_f32_16x16x32_bf16 v[106:109], v[164:167], v[188:191], v[106:109]
	v_mfma_f32_16x16x32_bf16 v[98:101], v[168:171], v[184:187], v[98:101]
	v_mfma_f32_16x16x32_bf16 v[98:101], v[172:175], v[188:191], v[98:101]
	v_mfma_f32_16x16x32_bf16 v[90:93], v[160:163], v[192:195], v[90:93]
	v_mfma_f32_16x16x32_bf16 v[90:93], v[164:167], v[196:199], v[90:93]
	v_mfma_f32_16x16x32_bf16 v[82:85], v[168:171], v[192:195], v[82:85]
	v_mfma_f32_16x16x32_bf16 v[82:85], v[172:175], v[196:199], v[82:85]
	s_setprio 3
	s_barrier
	v_mfma_f32_16x16x32_bf16 v[74:77], v[160:163], v[200:203], v[74:77]
	v_mfma_f32_16x16x32_bf16 v[74:77], v[164:167], v[204:207], v[74:77]
	v_mfma_f32_16x16x32_bf16 v[66:69], v[168:171], v[200:203], v[66:69]
	v_mfma_f32_16x16x32_bf16 v[66:69], v[172:175], v[204:207], v[66:69]
	s_setprio 0
	s_add_i32 s34, s34, s47
	v_lshl_add_u64 v[138:139], s[26:27], 0, v[0:1]
	s_mov_b32 m0, s34
	ds_read_b128 v[176:179], v143 offset:16384
	ds_read_b128 v[180:183], v143 offset:17408
	ds_read_b128 v[184:187], v143 offset:18432
	ds_read_b128 v[188:191], v143 offset:19456
	ds_read_b128 v[192:195], v143 offset:20480
	ds_read_b128 v[196:199], v143 offset:21504
	ds_read_b128 v[200:203], v143 offset:22528
	ds_read_b128 v[204:207], v143 offset:23552
	global_load_lds_dwordx4 v[138:139], off
	s_add_i32 m0, s34, 0x2000
	s_add_u32 s34, s26, 0x40000
	v_lshl_add_u64 v[208:209], s[26:27], 0, v[130:131]
	s_addc_u32 s35, s27, 0
	s_add_i32 s40, s40, s47
	global_load_lds_dwordx4 v[208:209], off
	v_lshl_add_u64 v[222:223], s[34:35], 0, v[0:1]
	s_mov_b32 m0, s40
	v_lshl_add_u64 v[224:225], s[30:31], 0, v[130:131]
	global_load_lds_dwordx4 v[222:223], off
	v_lshl_add_u64 v[222:223], s[34:35], 0, v[130:131]
	s_add_i32 m0, s40, 0x2000
	s_nop 0
	global_load_lds_dwordx4 v[222:223], off
	v_lshl_add_u64 v[222:223], s[30:31], 0, v[0:1]
	s_mov_b32 m0, s53
	s_nop 0
	global_load_lds_dwordx4 v[222:223], off
	s_mov_b32 m0, s64
	s_nop 0
	global_load_lds_dwordx4 v[224:225], off
	s_waitcnt vmcnt(8)
	s_waitcnt lgkmcnt(0)
	s_barrier
	s_setprio 1
	s_waitcnt lgkmcnt(0)
	v_mfma_f32_16x16x32_bf16 v[62:65], v[144:147], v[176:179], v[62:65]
	v_mfma_f32_16x16x32_bf16 v[62:65], v[148:151], v[180:183], v[62:65]
	v_mfma_f32_16x16x32_bf16 v[54:57], v[152:155], v[176:179], v[54:57]
	v_mfma_f32_16x16x32_bf16 v[54:57], v[156:159], v[180:183], v[54:57]
	v_mfma_f32_16x16x32_bf16 v[46:49], v[144:147], v[184:187], v[46:49]
	v_mfma_f32_16x16x32_bf16 v[46:49], v[148:151], v[188:191], v[46:49]
	v_mfma_f32_16x16x32_bf16 v[38:41], v[152:155], v[184:187], v[38:41]
	v_mfma_f32_16x16x32_bf16 v[38:41], v[156:159], v[188:191], v[38:41]
	v_mfma_f32_16x16x32_bf16 v[30:33], v[144:147], v[192:195], v[30:33]
	v_mfma_f32_16x16x32_bf16 v[30:33], v[148:151], v[196:199], v[30:33]
	v_mfma_f32_16x16x32_bf16 v[22:25], v[152:155], v[192:195], v[22:25]
	v_mfma_f32_16x16x32_bf16 v[22:25], v[156:159], v[196:199], v[22:25]
	v_mfma_f32_16x16x32_bf16 v[14:17], v[144:147], v[200:203], v[14:17]
	v_mfma_f32_16x16x32_bf16 v[14:17], v[148:151], v[204:207], v[14:17]
	v_mfma_f32_16x16x32_bf16 v[6:9], v[152:155], v[200:203], v[6:9]
	v_mfma_f32_16x16x32_bf16 v[6:9], v[156:159], v[204:207], v[6:9]
	s_setprio 0
	s_setprio 1
	v_mfma_f32_16x16x32_bf16 v[58:61], v[160:163], v[176:179], v[58:61]
	v_mfma_f32_16x16x32_bf16 v[58:61], v[164:167], v[180:183], v[58:61]
	v_mfma_f32_16x16x32_bf16 v[50:53], v[168:171], v[176:179], v[50:53]
	v_mfma_f32_16x16x32_bf16 v[50:53], v[172:175], v[180:183], v[50:53]
	v_mfma_f32_16x16x32_bf16 v[42:45], v[160:163], v[184:187], v[42:45]
	v_mfma_f32_16x16x32_bf16 v[42:45], v[164:167], v[188:191], v[42:45]
	v_mfma_f32_16x16x32_bf16 v[34:37], v[168:171], v[184:187], v[34:37]
	v_mfma_f32_16x16x32_bf16 v[34:37], v[172:175], v[188:191], v[34:37]
	v_mfma_f32_16x16x32_bf16 v[26:29], v[160:163], v[192:195], v[26:29]
	v_mfma_f32_16x16x32_bf16 v[26:29], v[164:167], v[196:199], v[26:29]
	v_mfma_f32_16x16x32_bf16 v[18:21], v[168:171], v[192:195], v[18:21]
	v_mfma_f32_16x16x32_bf16 v[18:21], v[172:175], v[196:199], v[18:21]
	s_setprio 3
	s_barrier
	v_mfma_f32_16x16x32_bf16 v[10:13], v[160:163], v[200:203], v[10:13]
	v_mfma_f32_16x16x32_bf16 v[10:13], v[164:167], v[204:207], v[10:13]
	v_mfma_f32_16x16x32_bf16 v[2:5], v[168:171], v[200:203], v[2:5]
	v_mfma_f32_16x16x32_bf16 v[2:5], v[172:175], v[204:207], v[2:5]
	s_setprio 0
	s_add_i32 s34, 0, 0x18000
	s_add_i32 s35, 0, 0x1c000
	v_add_u32_e32 v156, s34, v141
	v_add_u32_e32 v172, s35, v141
	ds_read_b128 v[144:147], v156
	ds_read_b128 v[148:151], v156 offset:1024
	ds_read_b128 v[152:155], v156 offset:2048
	ds_read_b128 v[156:159], v156 offset:3072
	ds_read_b128 v[160:163], v172
	ds_read_b128 v[164:167], v172 offset:1024
	ds_read_b128 v[168:171], v172 offset:2048
	ds_read_b128 v[172:175], v172 offset:3072
	s_add_u32 s30, s30, 0x40000
	s_addc_u32 s31, s31, 0
	s_mov_b32 m0, s65
	v_lshl_add_u64 v[226:227], s[30:31], 0, v[0:1]
	ds_read_b128 v[176:179], v143 offset:32768
	ds_read_b128 v[180:183], v143 offset:33792
	ds_read_b128 v[184:187], v143 offset:34816
	ds_read_b128 v[188:191], v143 offset:35840
	ds_read_b128 v[192:195], v143 offset:36864
	ds_read_b128 v[196:199], v143 offset:37888
	ds_read_b128 v[200:203], v143 offset:38912
	ds_read_b128 v[204:207], v143 offset:39936
	global_load_lds_dwordx4 v[226:227], off
	v_lshl_add_u64 v[226:227], s[30:31], 0, v[130:131]
	s_mov_b32 m0, s68
	s_nop 0
	global_load_lds_dwordx4 v[226:227], off
	s_waitcnt vmcnt(8)
	s_waitcnt lgkmcnt(0)
	s_barrier
	s_setprio 1
	s_waitcnt lgkmcnt(0)
	v_mfma_f32_16x16x32_bf16 v[126:129], v[144:147], v[176:179], v[126:129]
	v_mfma_f32_16x16x32_bf16 v[126:129], v[148:151], v[180:183], v[126:129]
	v_mfma_f32_16x16x32_bf16 v[118:121], v[152:155], v[176:179], v[118:121]
	v_mfma_f32_16x16x32_bf16 v[118:121], v[156:159], v[180:183], v[118:121]
	v_mfma_f32_16x16x32_bf16 v[110:113], v[144:147], v[184:187], v[110:113]
	v_mfma_f32_16x16x32_bf16 v[110:113], v[148:151], v[188:191], v[110:113]
	v_mfma_f32_16x16x32_bf16 v[102:105], v[152:155], v[184:187], v[102:105]
	v_mfma_f32_16x16x32_bf16 v[102:105], v[156:159], v[188:191], v[102:105]
	v_mfma_f32_16x16x32_bf16 v[94:97], v[144:147], v[192:195], v[94:97]
	v_mfma_f32_16x16x32_bf16 v[94:97], v[148:151], v[196:199], v[94:97]
	v_mfma_f32_16x16x32_bf16 v[86:89], v[152:155], v[192:195], v[86:89]
	v_mfma_f32_16x16x32_bf16 v[86:89], v[156:159], v[196:199], v[86:89]
	v_mfma_f32_16x16x32_bf16 v[78:81], v[144:147], v[200:203], v[78:81]
	v_mfma_f32_16x16x32_bf16 v[78:81], v[148:151], v[204:207], v[78:81]
	v_mfma_f32_16x16x32_bf16 v[70:73], v[152:155], v[200:203], v[70:73]
	v_mfma_f32_16x16x32_bf16 v[70:73], v[156:159], v[204:207], v[70:73]
	s_setprio 0
	s_setprio 1
	v_mfma_f32_16x16x32_bf16 v[122:125], v[160:163], v[176:179], v[122:125]
	v_mfma_f32_16x16x32_bf16 v[122:125], v[164:167], v[180:183], v[122:125]
	v_mfma_f32_16x16x32_bf16 v[114:117], v[168:171], v[176:179], v[114:117]
	v_mfma_f32_16x16x32_bf16 v[114:117], v[172:175], v[180:183], v[114:117]
	v_mfma_f32_16x16x32_bf16 v[106:109], v[160:163], v[184:187], v[106:109]
	v_mfma_f32_16x16x32_bf16 v[106:109], v[164:167], v[188:191], v[106:109]
	v_mfma_f32_16x16x32_bf16 v[98:101], v[168:171], v[184:187], v[98:101]
	v_mfma_f32_16x16x32_bf16 v[98:101], v[172:175], v[188:191], v[98:101]
	v_mfma_f32_16x16x32_bf16 v[90:93], v[160:163], v[192:195], v[90:93]
	v_mfma_f32_16x16x32_bf16 v[90:93], v[164:167], v[196:199], v[90:93]
	v_mfma_f32_16x16x32_bf16 v[82:85], v[168:171], v[192:195], v[82:85]
	v_mfma_f32_16x16x32_bf16 v[82:85], v[172:175], v[196:199], v[82:85]
	s_setprio 3
	s_barrier
	v_mfma_f32_16x16x32_bf16 v[74:77], v[160:163], v[200:203], v[74:77]
	v_mfma_f32_16x16x32_bf16 v[74:77], v[164:167], v[204:207], v[74:77]
	v_mfma_f32_16x16x32_bf16 v[66:69], v[168:171], v[200:203], v[66:69]
	v_mfma_f32_16x16x32_bf16 v[66:69], v[172:175], v[204:207], v[66:69]
	s_setprio 0
	s_add_i32 s30, s34, s47
	v_lshl_add_u64 v[138:139], v[138:139], 0, s[22:23]
	s_mov_b32 m0, s30
	ds_read_b128 v[176:179], v143 offset:49152
	ds_read_b128 v[180:183], v143 offset:50176
	ds_read_b128 v[184:187], v143 offset:51200
	ds_read_b128 v[188:191], v143 offset:52224
	ds_read_b128 v[192:195], v143 offset:53248
	ds_read_b128 v[196:199], v143 offset:54272
	ds_read_b128 v[200:203], v143 offset:55296
	ds_read_b128 v[204:207], v143 offset:56320
	global_load_lds_dwordx4 v[138:139], off
	s_add_i32 m0, s30, 0x2000
	s_add_u32 s26, s26, 0x40080
	v_lshl_add_u64 v[138:139], v[208:209], 0, s[22:23]
	s_addc_u32 s27, s27, 0
	s_add_i32 s30, s35, s47
	global_load_lds_dwordx4 v[138:139], off
	v_lshl_add_u64 v[138:139], s[26:27], 0, v[0:1]
	s_mov_b32 m0, s30
	s_nop 0
	global_load_lds_dwordx4 v[138:139], off
	v_lshl_add_u64 v[138:139], s[26:27], 0, v[130:131]
	s_add_i32 m0, s30, 0x2000
	s_nop 0
	global_load_lds_dwordx4 v[138:139], off
	v_lshl_add_u64 v[138:139], v[222:223], 0, s[22:23]
	s_mov_b32 m0, s69
	s_nop 0
	global_load_lds_dwordx4 v[138:139], off
	v_lshl_add_u64 v[138:139], v[224:225], 0, s[22:23]
	s_mov_b32 m0, s70
	s_nop 0
	global_load_lds_dwordx4 v[138:139], off
	s_waitcnt vmcnt(8)
	s_waitcnt lgkmcnt(0)
	s_barrier
	s_setprio 1
	s_waitcnt lgkmcnt(0)
	v_mfma_f32_16x16x32_bf16 v[62:65], v[144:147], v[176:179], v[62:65]
	v_mfma_f32_16x16x32_bf16 v[62:65], v[148:151], v[180:183], v[62:65]
	v_mfma_f32_16x16x32_bf16 v[54:57], v[152:155], v[176:179], v[54:57]
	v_mfma_f32_16x16x32_bf16 v[54:57], v[156:159], v[180:183], v[54:57]
	v_mfma_f32_16x16x32_bf16 v[46:49], v[144:147], v[184:187], v[46:49]
	v_mfma_f32_16x16x32_bf16 v[46:49], v[148:151], v[188:191], v[46:49]
	v_mfma_f32_16x16x32_bf16 v[38:41], v[152:155], v[184:187], v[38:41]
	v_mfma_f32_16x16x32_bf16 v[38:41], v[156:159], v[188:191], v[38:41]
	v_mfma_f32_16x16x32_bf16 v[30:33], v[144:147], v[192:195], v[30:33]
	v_mfma_f32_16x16x32_bf16 v[30:33], v[148:151], v[196:199], v[30:33]
	v_mfma_f32_16x16x32_bf16 v[22:25], v[152:155], v[192:195], v[22:25]
	v_mfma_f32_16x16x32_bf16 v[22:25], v[156:159], v[196:199], v[22:25]
	v_mfma_f32_16x16x32_bf16 v[14:17], v[144:147], v[200:203], v[14:17]
	v_mfma_f32_16x16x32_bf16 v[14:17], v[148:151], v[204:207], v[14:17]
	v_mfma_f32_16x16x32_bf16 v[6:9], v[152:155], v[200:203], v[6:9]
	v_mfma_f32_16x16x32_bf16 v[6:9], v[156:159], v[204:207], v[6:9]
	s_setprio 0
	s_setprio 1
	v_mfma_f32_16x16x32_bf16 v[58:61], v[160:163], v[176:179], v[58:61]
	v_mfma_f32_16x16x32_bf16 v[58:61], v[164:167], v[180:183], v[58:61]
	v_mfma_f32_16x16x32_bf16 v[50:53], v[168:171], v[176:179], v[50:53]
	v_mfma_f32_16x16x32_bf16 v[50:53], v[172:175], v[180:183], v[50:53]
	v_mfma_f32_16x16x32_bf16 v[42:45], v[160:163], v[184:187], v[42:45]
	v_mfma_f32_16x16x32_bf16 v[42:45], v[164:167], v[188:191], v[42:45]
	v_mfma_f32_16x16x32_bf16 v[34:37], v[168:171], v[184:187], v[34:37]
	v_mfma_f32_16x16x32_bf16 v[34:37], v[172:175], v[188:191], v[34:37]
	v_mfma_f32_16x16x32_bf16 v[26:29], v[160:163], v[192:195], v[26:29]
	v_mfma_f32_16x16x32_bf16 v[26:29], v[164:167], v[196:199], v[26:29]
	v_mfma_f32_16x16x32_bf16 v[18:21], v[168:171], v[192:195], v[18:21]
	v_mfma_f32_16x16x32_bf16 v[18:21], v[172:175], v[196:199], v[18:21]
	s_setprio 3
	s_barrier
	v_mfma_f32_16x16x32_bf16 v[10:13], v[160:163], v[200:203], v[10:13]
	v_mfma_f32_16x16x32_bf16 v[10:13], v[164:167], v[204:207], v[10:13]
	v_mfma_f32_16x16x32_bf16 v[2:5], v[168:171], v[200:203], v[2:5]
	v_mfma_f32_16x16x32_bf16 v[2:5], v[172:175], v[204:207], v[2:5]
	s_setprio 0
	s_add_i32 s37, s37, 2
	s_add_u32 s16, s16, 0x100
	s_addc_u32 s17, s17, 0
	s_add_u32 s29, s29, 0x100
	s_addc_u32 s36, s36, 0
	s_cmp_gt_u32 s37, 13
	s_cbranch_scc0 .LBB0_143
	s_and_b64 vcc, exec, s[2:3]
	s_cbranch_vccz .LBB0_146
	s_barrier

.LBB0_233:
	s_add_u32 s4, s0, 0xfffc0080
	s_addc_u32 s5, s1, -1
	s_add_i32 s18, 0, 0x10000
	s_cmp_eq_u32 s17, 12
	s_cselect_b32 s9, s3, s5
	s_cselect_b32 s8, s11, s4
	v_add_u32_e32 v0, s18, v191
	s_cselect_b32 s5, s12, s15
	s_cselect_b32 s4, s13, s14
	s_add_i32 s25, 0, 0x14000
	ds_read_b128 v[2:5], v0
	ds_read_b128 v[6:9], v0 offset:1024
	ds_read_b128 v[10:13], v0 offset:2048
	ds_read_b128 v[14:17], v0 offset:3072
	v_add_u32_e32 v0, s25, v191
	ds_read_b128 v[146:149], v0
	ds_read_b128 v[150:153], v0 offset:1024
	ds_read_b128 v[154:157], v0 offset:2048
	ds_read_b128 v[158:161], v0 offset:3072
	v_lshl_add_u64 v[230:231], s[0:1], 0, v[178:179]
	s_add_i32 m0, s65, 0xc000
	ds_read_b128 v[162:165], v200
	ds_read_b128 v[166:169], v200 offset:1024
	ds_read_b128 v[182:185], v200 offset:2048
	ds_read_b128 v[186:189], v200 offset:3072
	ds_read_b128 v[202:205], v200 offset:4096
	ds_read_b128 v[206:209], v200 offset:5120
	ds_read_b128 v[222:225], v200 offset:6144
	ds_read_b128 v[226:229], v200 offset:7168
	global_load_lds_dwordx4 v[230:231], off
	v_lshl_add_u64 v[230:231], s[0:1], 0, v[180:181]
	s_add_i32 m0, s65, 0xe000
	s_nop 0
	global_load_lds_dwordx4 v[230:231], off
	s_waitcnt vmcnt(8)
	s_waitcnt lgkmcnt(0)
	s_barrier
	s_setprio 1
	s_waitcnt lgkmcnt(0)
	v_mfma_f32_16x16x32_bf16 v[142:145], v[2:5], v[162:165], v[142:145]
	v_mfma_f32_16x16x32_bf16 v[142:145], v[6:9], v[166:169], v[142:145]
	v_mfma_f32_16x16x32_bf16 v[138:141], v[10:13], v[162:165], v[138:141]
	v_mfma_f32_16x16x32_bf16 v[138:141], v[14:17], v[166:169], v[138:141]
	v_mfma_f32_16x16x32_bf16 v[134:137], v[2:5], v[182:185], v[134:137]
	v_mfma_f32_16x16x32_bf16 v[134:137], v[6:9], v[186:189], v[134:137]
	v_mfma_f32_16x16x32_bf16 v[126:129], v[10:13], v[182:185], v[126:129]
	v_mfma_f32_16x16x32_bf16 v[126:129], v[14:17], v[186:189], v[126:129]
	v_mfma_f32_16x16x32_bf16 v[118:121], v[2:5], v[202:205], v[118:121]
	v_mfma_f32_16x16x32_bf16 v[118:121], v[6:9], v[206:209], v[118:121]
	v_mfma_f32_16x16x32_bf16 v[110:113], v[10:13], v[202:205], v[110:113]
	v_mfma_f32_16x16x32_bf16 v[110:113], v[14:17], v[206:209], v[110:113]
	v_mfma_f32_16x16x32_bf16 v[102:105], v[2:5], v[222:225], v[102:105]
	v_mfma_f32_16x16x32_bf16 v[102:105], v[6:9], v[226:229], v[102:105]
	v_mfma_f32_16x16x32_bf16 v[94:97], v[10:13], v[222:225], v[94:97]
	v_mfma_f32_16x16x32_bf16 v[94:97], v[14:17], v[226:229], v[94:97]
	s_setprio 0
	s_setprio 1
	v_mfma_f32_16x16x32_bf16 v[130:133], v[146:149], v[162:165], v[130:133]
	v_mfma_f32_16x16x32_bf16 v[130:133], v[150:153], v[166:169], v[130:133]
	v_mfma_f32_16x16x32_bf16 v[122:125], v[154:157], v[162:165], v[122:125]
	v_mfma_f32_16x16x32_bf16 v[122:125], v[158:161], v[166:169], v[122:125]
	v_mfma_f32_16x16x32_bf16 v[114:117], v[146:149], v[182:185], v[114:117]
	v_mfma_f32_16x16x32_bf16 v[114:117], v[150:153], v[186:189], v[114:117]
	v_mfma_f32_16x16x32_bf16 v[106:109], v[154:157], v[182:185], v[106:109]
	v_mfma_f32_16x16x32_bf16 v[106:109], v[158:161], v[186:189], v[106:109]
	v_mfma_f32_16x16x32_bf16 v[98:101], v[146:149], v[202:205], v[98:101]
	v_mfma_f32_16x16x32_bf16 v[98:101], v[150:153], v[206:209], v[98:101]
	v_mfma_f32_16x16x32_bf16 v[90:93], v[154:157], v[202:205], v[90:93]
	v_mfma_f32_16x16x32_bf16 v[90:93], v[158:161], v[206:209], v[90:93]
	s_setprio 3
	s_barrier
	v_mfma_f32_16x16x32_bf16 v[86:89], v[146:149], v[222:225], v[86:89]
	v_mfma_f32_16x16x32_bf16 v[86:89], v[150:153], v[226:229], v[86:89]
	v_mfma_f32_16x16x32_bf16 v[82:85], v[154:157], v[222:225], v[82:85]
	v_mfma_f32_16x16x32_bf16 v[82:85], v[158:161], v[226:229], v[82:85]
	s_setprio 0
	s_add_i32 s18, s18, s64
	v_lshl_add_u64 v[230:231], s[4:5], 0, v[172:173]
	s_mov_b32 m0, s18
	ds_read_b128 v[162:165], v200 offset:16384
	ds_read_b128 v[166:169], v200 offset:17408
	ds_read_b128 v[182:185], v200 offset:18432
	ds_read_b128 v[186:189], v200 offset:19456
	ds_read_b128 v[202:205], v200 offset:20480
	ds_read_b128 v[206:209], v200 offset:21504
	ds_read_b128 v[222:225], v200 offset:22528
	ds_read_b128 v[226:229], v200 offset:23552
	global_load_lds_dwordx4 v[230:231], off
	s_add_i32 m0, s18, 0x2000
	s_add_u32 s18, s4, 0x40000
	v_lshl_add_u64 v[232:233], s[4:5], 0, v[170:171]
	s_addc_u32 s19, s5, 0
	s_add_i32 s25, s25, s64
	global_load_lds_dwordx4 v[232:233], off
	v_lshl_add_u64 v[246:247], s[18:19], 0, v[172:173]
	s_mov_b32 m0, s25
	v_lshl_add_u64 v[248:249], s[8:9], 0, v[170:171]
	global_load_lds_dwordx4 v[246:247], off
	v_lshl_add_u64 v[246:247], s[18:19], 0, v[170:171]
	s_add_i32 m0, s25, 0x2000
	s_nop 0
	global_load_lds_dwordx4 v[246:247], off
	v_lshl_add_u64 v[246:247], s[8:9], 0, v[172:173]
	s_mov_b32 m0, s65
	s_nop 0
	global_load_lds_dwordx4 v[246:247], off
	s_mov_b32 m0, s68
	s_nop 0
	global_load_lds_dwordx4 v[248:249], off
	s_waitcnt vmcnt(8)
	s_waitcnt lgkmcnt(0)
	s_barrier
	s_setprio 1
	s_waitcnt lgkmcnt(0)
	v_mfma_f32_16x16x32_bf16 v[78:81], v[2:5], v[162:165], v[78:81]
	v_mfma_f32_16x16x32_bf16 v[74:77], v[10:13], v[162:165], v[74:77]
	v_mfma_f32_16x16x32_bf16 v[70:73], v[2:5], v[182:185], v[70:73]
	v_mfma_f32_16x16x32_bf16 v[62:65], v[10:13], v[182:185], v[62:65]
	v_mfma_f32_16x16x32_bf16 v[54:57], v[2:5], v[202:205], v[54:57]
	v_mfma_f32_16x16x32_bf16 v[46:49], v[10:13], v[202:205], v[46:49]
	v_mfma_f32_16x16x32_bf16 v[2:5], v[2:5], v[222:225], v[38:41]
	v_mfma_f32_16x16x32_bf16 v[78:81], v[6:9], v[166:169], v[78:81]
	v_mfma_f32_16x16x32_bf16 v[74:77], v[14:17], v[166:169], v[74:77]
	v_mfma_f32_16x16x32_bf16 v[70:73], v[6:9], v[186:189], v[70:73]
	v_mfma_f32_16x16x32_bf16 v[62:65], v[14:17], v[186:189], v[62:65]
	v_mfma_f32_16x16x32_bf16 v[54:57], v[6:9], v[206:209], v[54:57]
	v_mfma_f32_16x16x32_bf16 v[46:49], v[14:17], v[206:209], v[46:49]
	v_mfma_f32_16x16x32_bf16 v[2:5], v[6:9], v[226:229], v[2:5]
	v_mfma_f32_16x16x32_bf16 v[6:9], v[10:13], v[222:225], v[30:33]
	v_mfma_f32_16x16x32_bf16 v[6:9], v[14:17], v[226:229], v[6:9]
	s_setprio 0
	s_setprio 1
	v_mfma_f32_16x16x32_bf16 v[30:33], v[146:149], v[182:185], v[50:53]
	v_mfma_f32_16x16x32_bf16 v[50:53], v[150:153], v[186:189], v[30:33]
	v_mfma_f32_16x16x32_bf16 v[30:33], v[154:157], v[182:185], v[42:45]
	v_mfma_f32_16x16x32_bf16 v[42:45], v[158:161], v[186:189], v[30:33]
	v_mfma_f32_16x16x32_bf16 v[30:33], v[146:149], v[202:205], v[34:37]
	v_mfma_f32_16x16x32_bf16 v[26:29], v[154:157], v[202:205], v[26:29]
	v_mfma_f32_16x16x32_bf16 v[22:25], v[146:149], v[222:225], v[22:25]
	v_mfma_f32_16x16x32_bf16 v[18:21], v[154:157], v[222:225], v[18:21]
	v_mfma_f32_16x16x32_bf16 v[10:13], v[146:149], v[162:165], v[66:69]
	v_mfma_f32_16x16x32_bf16 v[14:17], v[154:157], v[162:165], v[58:61]
	v_mfma_f32_16x16x32_bf16 v[34:37], v[150:153], v[206:209], v[30:33]
	v_mfma_f32_16x16x32_bf16 v[26:29], v[158:161], v[206:209], v[26:29]
	s_setprio 3
	s_barrier
	v_mfma_f32_16x16x32_bf16 v[22:25], v[150:153], v[226:229], v[22:25]
	v_mfma_f32_16x16x32_bf16 v[18:21], v[158:161], v[226:229], v[18:21]
	v_mfma_f32_16x16x32_bf16 v[10:13], v[150:153], v[166:169], v[10:13]
	v_mfma_f32_16x16x32_bf16 v[14:17], v[158:161], v[166:169], v[14:17]
	s_setprio 0
	s_add_i32 s18, 0, 0x18000
	v_add_u32_e32 v0, s18, v191
	s_add_i32 s19, 0, 0x1c000
	ds_read_b128 v[30:33], v0
	ds_read_b128 v[38:41], v0 offset:1024
	ds_read_b128 v[58:61], v0 offset:2048
	ds_read_b128 v[66:69], v0 offset:3072
	v_add_u32_e32 v0, s19, v191
	ds_read_b128 v[146:149], v0
	ds_read_b128 v[150:153], v0 offset:1024
	ds_read_b128 v[154:157], v0 offset:2048
	ds_read_b128 v[158:161], v0 offset:3072
	s_add_u32 s8, s8, 0x40000
	s_addc_u32 s9, s9, 0
	s_mov_b32 m0, s69
	v_lshl_add_u64 v[250:251], s[8:9], 0, v[172:173]
	ds_read_b128 v[162:165], v200 offset:32768
	ds_read_b128 v[166:169], v200 offset:33792
	ds_read_b128 v[182:185], v200 offset:34816
	ds_read_b128 v[186:189], v200 offset:35840
	ds_read_b128 v[202:205], v200 offset:36864
	ds_read_b128 v[206:209], v200 offset:37888
	ds_read_b128 v[222:225], v200 offset:38912
	ds_read_b128 v[226:229], v200 offset:39936
	global_load_lds_dwordx4 v[250:251], off
	v_lshl_add_u64 v[250:251], s[8:9], 0, v[170:171]
	s_mov_b32 m0, s70
	s_nop 0
	global_load_lds_dwordx4 v[250:251], off
	s_waitcnt vmcnt(8)
	s_waitcnt lgkmcnt(0)
	s_barrier
	s_setprio 1
	s_waitcnt lgkmcnt(0)
	v_mfma_f32_16x16x32_bf16 v[142:145], v[30:33], v[162:165], v[142:145]
	v_mfma_f32_16x16x32_bf16 v[142:145], v[38:41], v[166:169], v[142:145]
	v_mfma_f32_16x16x32_bf16 v[138:141], v[58:61], v[162:165], v[138:141]
	v_mfma_f32_16x16x32_bf16 v[138:141], v[66:69], v[166:169], v[138:141]
	v_mfma_f32_16x16x32_bf16 v[134:137], v[30:33], v[182:185], v[134:137]
	v_mfma_f32_16x16x32_bf16 v[134:137], v[38:41], v[186:189], v[134:137]
	v_mfma_f32_16x16x32_bf16 v[126:129], v[58:61], v[182:185], v[126:129]
	v_mfma_f32_16x16x32_bf16 v[126:129], v[66:69], v[186:189], v[126:129]
	v_mfma_f32_16x16x32_bf16 v[118:121], v[30:33], v[202:205], v[118:121]
	v_mfma_f32_16x16x32_bf16 v[118:121], v[38:41], v[206:209], v[118:121]
	v_mfma_f32_16x16x32_bf16 v[110:113], v[58:61], v[202:205], v[110:113]
	v_mfma_f32_16x16x32_bf16 v[110:113], v[66:69], v[206:209], v[110:113]
	v_mfma_f32_16x16x32_bf16 v[102:105], v[30:33], v[222:225], v[102:105]
	v_mfma_f32_16x16x32_bf16 v[102:105], v[38:41], v[226:229], v[102:105]
	v_mfma_f32_16x16x32_bf16 v[94:97], v[58:61], v[222:225], v[94:97]
	v_mfma_f32_16x16x32_bf16 v[94:97], v[66:69], v[226:229], v[94:97]
	s_setprio 0
	s_setprio 1
	v_mfma_f32_16x16x32_bf16 v[130:133], v[146:149], v[162:165], v[130:133]
	v_mfma_f32_16x16x32_bf16 v[130:133], v[150:153], v[166:169], v[130:133]
	v_mfma_f32_16x16x32_bf16 v[122:125], v[154:157], v[162:165], v[122:125]
	v_mfma_f32_16x16x32_bf16 v[122:125], v[158:161], v[166:169], v[122:125]
	v_mfma_f32_16x16x32_bf16 v[114:117], v[146:149], v[182:185], v[114:117]
	v_mfma_f32_16x16x32_bf16 v[114:117], v[150:153], v[186:189], v[114:117]
	v_mfma_f32_16x16x32_bf16 v[106:109], v[154:157], v[182:185], v[106:109]
	v_mfma_f32_16x16x32_bf16 v[106:109], v[158:161], v[186:189], v[106:109]
	v_mfma_f32_16x16x32_bf16 v[98:101], v[146:149], v[202:205], v[98:101]
	v_mfma_f32_16x16x32_bf16 v[98:101], v[150:153], v[206:209], v[98:101]
	v_mfma_f32_16x16x32_bf16 v[90:93], v[154:157], v[202:205], v[90:93]
	v_mfma_f32_16x16x32_bf16 v[90:93], v[158:161], v[206:209], v[90:93]
	s_setprio 3
	s_barrier
	v_mfma_f32_16x16x32_bf16 v[86:89], v[146:149], v[222:225], v[86:89]
	v_mfma_f32_16x16x32_bf16 v[86:89], v[150:153], v[226:229], v[86:89]
	v_mfma_f32_16x16x32_bf16 v[82:85], v[154:157], v[222:225], v[82:85]
	v_mfma_f32_16x16x32_bf16 v[82:85], v[158:161], v[226:229], v[82:85]
	s_setprio 0
	s_add_i32 s8, s18, s64
	v_lshl_add_u64 v[230:231], v[230:231], 0, s[22:23]
	s_mov_b32 m0, s8
	ds_read_b128 v[162:165], v200 offset:49152
	ds_read_b128 v[166:169], v200 offset:50176
	ds_read_b128 v[182:185], v200 offset:51200
	ds_read_b128 v[186:189], v200 offset:52224
	ds_read_b128 v[202:205], v200 offset:53248
	ds_read_b128 v[206:209], v200 offset:54272
	ds_read_b128 v[222:225], v200 offset:55296
	ds_read_b128 v[226:229], v200 offset:56320
	global_load_lds_dwordx4 v[230:231], off
	s_add_i32 m0, s8, 0x2000
	s_add_u32 s4, s4, 0x40080
	v_lshl_add_u64 v[230:231], v[232:233], 0, s[22:23]
	s_addc_u32 s5, s5, 0
	s_add_i32 s8, s19, s64
	global_load_lds_dwordx4 v[230:231], off
	v_lshl_add_u64 v[230:231], s[4:5], 0, v[172:173]
	s_mov_b32 m0, s8
	s_nop 0
	global_load_lds_dwordx4 v[230:231], off
	v_lshl_add_u64 v[230:231], s[4:5], 0, v[170:171]
	s_add_i32 m0, s8, 0x2000
	s_nop 0
	global_load_lds_dwordx4 v[230:231], off
	v_lshl_add_u64 v[230:231], v[246:247], 0, s[22:23]
	s_mov_b32 m0, s94
	s_nop 0
	global_load_lds_dwordx4 v[230:231], off
	v_lshl_add_u64 v[230:231], v[248:249], 0, s[22:23]
	s_mov_b32 m0, s95
	s_nop 0
	global_load_lds_dwordx4 v[230:231], off
	s_waitcnt vmcnt(8)
	s_waitcnt lgkmcnt(0)
	s_barrier
	s_setprio 1
	s_waitcnt lgkmcnt(0)
	v_mfma_f32_16x16x32_bf16 v[78:81], v[30:33], v[162:165], v[78:81]
	v_mfma_f32_16x16x32_bf16 v[70:73], v[30:33], v[182:185], v[70:73]
	v_mfma_f32_16x16x32_bf16 v[54:57], v[30:33], v[202:205], v[54:57]
	v_mfma_f32_16x16x32_bf16 v[2:5], v[30:33], v[222:225], v[2:5]
	v_mfma_f32_16x16x32_bf16 v[78:81], v[38:41], v[166:169], v[78:81]
	v_mfma_f32_16x16x32_bf16 v[74:77], v[58:61], v[162:165], v[74:77]
	v_mfma_f32_16x16x32_bf16 v[70:73], v[38:41], v[186:189], v[70:73]
	v_mfma_f32_16x16x32_bf16 v[62:65], v[58:61], v[182:185], v[62:65]
	v_mfma_f32_16x16x32_bf16 v[54:57], v[38:41], v[206:209], v[54:57]
	v_mfma_f32_16x16x32_bf16 v[46:49], v[58:61], v[202:205], v[46:49]
	v_mfma_f32_16x16x32_bf16 v[38:41], v[38:41], v[226:229], v[2:5]
	v_mfma_f32_16x16x32_bf16 v[2:5], v[58:61], v[222:225], v[6:9]
	v_mfma_f32_16x16x32_bf16 v[74:77], v[66:69], v[166:169], v[74:77]
	v_mfma_f32_16x16x32_bf16 v[62:65], v[66:69], v[186:189], v[62:65]
	v_mfma_f32_16x16x32_bf16 v[46:49], v[66:69], v[206:209], v[46:49]
	v_mfma_f32_16x16x32_bf16 v[30:33], v[66:69], v[226:229], v[2:5]
	s_setprio 0
	s_setprio 1
	v_mfma_f32_16x16x32_bf16 v[2:5], v[146:149], v[162:165], v[10:13]
	v_mfma_f32_16x16x32_bf16 v[66:69], v[150:153], v[166:169], v[2:5]
	v_mfma_f32_16x16x32_bf16 v[2:5], v[154:157], v[162:165], v[14:17]
	v_mfma_f32_16x16x32_bf16 v[58:61], v[158:161], v[166:169], v[2:5]
	v_mfma_f32_16x16x32_bf16 v[2:5], v[146:149], v[182:185], v[50:53]
	v_mfma_f32_16x16x32_bf16 v[50:53], v[150:153], v[186:189], v[2:5]
	v_mfma_f32_16x16x32_bf16 v[2:5], v[154:157], v[182:185], v[42:45]
	v_mfma_f32_16x16x32_bf16 v[42:45], v[158:161], v[186:189], v[2:5]
	v_mfma_f32_16x16x32_bf16 v[2:5], v[146:149], v[202:205], v[34:37]
	v_mfma_f32_16x16x32_bf16 v[34:37], v[150:153], v[206:209], v[2:5]
	v_mfma_f32_16x16x32_bf16 v[2:5], v[154:157], v[202:205], v[26:29]
	v_mfma_f32_16x16x32_bf16 v[26:29], v[158:161], v[206:209], v[2:5]
	s_setprio 3
	s_barrier
	v_mfma_f32_16x16x32_bf16 v[2:5], v[146:149], v[222:225], v[22:25]
	v_mfma_f32_16x16x32_bf16 v[22:25], v[150:153], v[226:229], v[2:5]
	v_mfma_f32_16x16x32_bf16 v[2:5], v[154:157], v[222:225], v[18:21]
	v_mfma_f32_16x16x32_bf16 v[18:21], v[158:161], v[226:229], v[2:5]
	s_setprio 0
	s_add_i32 s17, s17, 2
	s_add_u32 s0, s0, 0x100
	s_addc_u32 s1, s1, 0
	s_add_u32 s14, s14, 0x100
	s_addc_u32 s15, s15, 0
	s_cmp_gt_u32 s17, 13
	s_cbranch_scc0 .LBB0_233
	s_and_b64 vcc, exec, s[78:79]
	s_cbranch_vccz .LBB0_236
	s_barrier

.LBB0_707:
	s_add_i32 s34, s68, 2
	s_add_u32 s35, s0, 0x80
	s_addc_u32 s69, s1, 0
	s_add_i32 s84, 0, 0x10000
	s_cmp_eq_u32 s96, s68
	s_cselect_b32 s69, s53, s69
	s_cselect_b32 s68, s52, s35
	s_cselect_b32 s89, s65, vcc_hi
	s_cselect_b32 s88, s64, vcc_lo
	s_add_i32 s35, 0, 0x14000
	v_add_u32_e32 v142, s84, v212
	v_add_u32_e32 v158, s35, v212
	ds_read_b128 v[130:133], v142
	ds_read_b128 v[134:137], v142 offset:1024
	ds_read_b128 v[138:141], v142 offset:2048
	ds_read_b128 v[142:145], v142 offset:3072
	ds_read_b128 v[146:149], v158
	ds_read_b128 v[150:153], v158 offset:1024
	ds_read_b128 v[154:157], v158 offset:2048
	ds_read_b128 v[158:161], v158 offset:3072
	v_lshl_add_u64 v[194:195], s[0:1], 0, v[224:225]
	s_add_i32 m0, s28, 0xc000
	ds_read_b128 v[162:165], v245
	ds_read_b128 v[166:169], v245 offset:1024
	ds_read_b128 v[170:173], v245 offset:2048
	ds_read_b128 v[174:177], v245 offset:3072
	ds_read_b128 v[178:181], v245 offset:4096
	ds_read_b128 v[182:185], v245 offset:5120
	ds_read_b128 v[186:189], v245 offset:6144
	ds_read_b128 v[190:193], v245 offset:7168
	global_load_lds_dwordx4 v[194:195], off
	v_lshl_add_u64 v[194:195], s[0:1], 0, v[226:227]
	s_add_i32 m0, s28, 0xe000
	s_nop 0
	global_load_lds_dwordx4 v[194:195], off
	s_waitcnt vmcnt(8)
	s_waitcnt lgkmcnt(0)
	s_barrier
	s_setprio 1
	s_waitcnt lgkmcnt(0)
	v_mfma_f32_16x16x32_bf16 v[126:129], v[130:133], v[162:165], v[126:129]
	v_mfma_f32_16x16x32_bf16 v[126:129], v[134:137], v[166:169], v[126:129]
	v_mfma_f32_16x16x32_bf16 v[122:125], v[138:141], v[162:165], v[122:125]
	v_mfma_f32_16x16x32_bf16 v[122:125], v[142:145], v[166:169], v[122:125]
	v_mfma_f32_16x16x32_bf16 v[114:117], v[130:133], v[170:173], v[114:117]
	v_mfma_f32_16x16x32_bf16 v[114:117], v[134:137], v[174:177], v[114:117]
	v_mfma_f32_16x16x32_bf16 v[106:109], v[138:141], v[170:173], v[106:109]
	v_mfma_f32_16x16x32_bf16 v[106:109], v[142:145], v[174:177], v[106:109]
	v_mfma_f32_16x16x32_bf16 v[98:101], v[130:133], v[178:181], v[98:101]
	v_mfma_f32_16x16x32_bf16 v[98:101], v[134:137], v[182:185], v[98:101]
	v_mfma_f32_16x16x32_bf16 v[90:93], v[138:141], v[178:181], v[90:93]
	v_mfma_f32_16x16x32_bf16 v[90:93], v[142:145], v[182:185], v[90:93]
	v_mfma_f32_16x16x32_bf16 v[82:85], v[130:133], v[186:189], v[82:85]
	v_mfma_f32_16x16x32_bf16 v[82:85], v[134:137], v[190:193], v[82:85]
	v_mfma_f32_16x16x32_bf16 v[74:77], v[138:141], v[186:189], v[74:77]
	v_mfma_f32_16x16x32_bf16 v[74:77], v[142:145], v[190:193], v[74:77]
	s_setprio 0
	s_setprio 1
	v_mfma_f32_16x16x32_bf16 v[118:121], v[146:149], v[162:165], v[118:121]
	v_mfma_f32_16x16x32_bf16 v[118:121], v[150:153], v[166:169], v[118:121]
	v_mfma_f32_16x16x32_bf16 v[110:113], v[154:157], v[162:165], v[110:113]
	v_mfma_f32_16x16x32_bf16 v[110:113], v[158:161], v[166:169], v[110:113]
	v_mfma_f32_16x16x32_bf16 v[102:105], v[146:149], v[170:173], v[102:105]
	v_mfma_f32_16x16x32_bf16 v[102:105], v[150:153], v[174:177], v[102:105]
	v_mfma_f32_16x16x32_bf16 v[94:97], v[154:157], v[170:173], v[94:97]
	v_mfma_f32_16x16x32_bf16 v[94:97], v[158:161], v[174:177], v[94:97]
	v_mfma_f32_16x16x32_bf16 v[86:89], v[146:149], v[178:181], v[86:89]
	v_mfma_f32_16x16x32_bf16 v[86:89], v[150:153], v[182:185], v[86:89]
	v_mfma_f32_16x16x32_bf16 v[78:81], v[154:157], v[178:181], v[78:81]
	v_mfma_f32_16x16x32_bf16 v[78:81], v[158:161], v[182:185], v[78:81]
	s_setprio 3
	s_barrier
	v_mfma_f32_16x16x32_bf16 v[70:73], v[146:149], v[186:189], v[70:73]
	v_mfma_f32_16x16x32_bf16 v[70:73], v[150:153], v[190:193], v[70:73]
	v_mfma_f32_16x16x32_bf16 v[66:69], v[154:157], v[186:189], v[66:69]
	v_mfma_f32_16x16x32_bf16 v[66:69], v[158:161], v[190:193], v[66:69]
	s_setprio 0
	s_add_i32 s84, s84, s19
	v_lshl_add_u64 v[194:195], s[88:89], 0, v[0:1]
	s_mov_b32 m0, s84
	ds_read_b128 v[162:165], v245 offset:16384
	ds_read_b128 v[166:169], v245 offset:17408
	ds_read_b128 v[170:173], v245 offset:18432
	ds_read_b128 v[174:177], v245 offset:19456
	ds_read_b128 v[178:181], v245 offset:20480
	ds_read_b128 v[182:185], v245 offset:21504
	ds_read_b128 v[186:189], v245 offset:22528
	ds_read_b128 v[190:193], v245 offset:23552
	global_load_lds_dwordx4 v[194:195], off
	s_add_i32 m0, s84, 0x2000
	v_lshl_add_u64 v[196:197], s[88:89], 0, v[222:223]
	s_add_u32 s88, s88, s2
	s_addc_u32 s89, s89, 0
	s_add_i32 s35, s35, s19
	global_load_lds_dwordx4 v[196:197], off
	v_lshl_add_u64 v[198:199], s[88:89], 0, v[0:1]
	s_mov_b32 m0, s35
	v_lshl_add_u64 v[200:201], s[88:89], 0, v[222:223]
	global_load_lds_dwordx4 v[198:199], off
	s_add_i32 m0, s35, 0x2000
	v_lshl_add_u64 v[202:203], s[68:69], 0, v[0:1]
	global_load_lds_dwordx4 v[200:201], off
	s_mov_b32 m0, s28
	v_lshl_add_u64 v[204:205], s[68:69], 0, v[222:223]
	global_load_lds_dwordx4 v[202:203], off
	s_mov_b32 m0, s29
	s_nop 0
	global_load_lds_dwordx4 v[204:205], off
	s_waitcnt vmcnt(8)
	s_waitcnt lgkmcnt(0)
	s_barrier
	s_setprio 1
	s_waitcnt lgkmcnt(0)
	v_mfma_f32_16x16x32_bf16 v[62:65], v[130:133], v[162:165], v[62:65]
	v_mfma_f32_16x16x32_bf16 v[62:65], v[134:137], v[166:169], v[62:65]
	v_mfma_f32_16x16x32_bf16 v[58:61], v[138:141], v[162:165], v[58:61]
	v_mfma_f32_16x16x32_bf16 v[58:61], v[142:145], v[166:169], v[58:61]
	v_mfma_f32_16x16x32_bf16 v[50:53], v[130:133], v[170:173], v[50:53]
	v_mfma_f32_16x16x32_bf16 v[50:53], v[134:137], v[174:177], v[50:53]
	v_mfma_f32_16x16x32_bf16 v[42:45], v[138:141], v[170:173], v[42:45]
	v_mfma_f32_16x16x32_bf16 v[42:45], v[142:145], v[174:177], v[42:45]
	v_mfma_f32_16x16x32_bf16 v[34:37], v[130:133], v[178:181], v[34:37]
	v_mfma_f32_16x16x32_bf16 v[34:37], v[134:137], v[182:185], v[34:37]
	v_mfma_f32_16x16x32_bf16 v[26:29], v[138:141], v[178:181], v[26:29]
	v_mfma_f32_16x16x32_bf16 v[26:29], v[142:145], v[182:185], v[26:29]
	v_mfma_f32_16x16x32_bf16 v[18:21], v[130:133], v[186:189], v[18:21]
	v_mfma_f32_16x16x32_bf16 v[18:21], v[134:137], v[190:193], v[18:21]
	v_mfma_f32_16x16x32_bf16 v[10:13], v[138:141], v[186:189], v[10:13]
	v_mfma_f32_16x16x32_bf16 v[10:13], v[142:145], v[190:193], v[10:13]
	s_setprio 0
	s_setprio 1
	v_mfma_f32_16x16x32_bf16 v[54:57], v[146:149], v[162:165], v[54:57]
	v_mfma_f32_16x16x32_bf16 v[54:57], v[150:153], v[166:169], v[54:57]
	v_mfma_f32_16x16x32_bf16 v[46:49], v[154:157], v[162:165], v[46:49]
	v_mfma_f32_16x16x32_bf16 v[46:49], v[158:161], v[166:169], v[46:49]
	v_mfma_f32_16x16x32_bf16 v[38:41], v[146:149], v[170:173], v[38:41]
	v_mfma_f32_16x16x32_bf16 v[38:41], v[150:153], v[174:177], v[38:41]
	v_mfma_f32_16x16x32_bf16 v[30:33], v[154:157], v[170:173], v[30:33]
	v_mfma_f32_16x16x32_bf16 v[30:33], v[158:161], v[174:177], v[30:33]
	v_mfma_f32_16x16x32_bf16 v[22:25], v[146:149], v[178:181], v[22:25]
	v_mfma_f32_16x16x32_bf16 v[22:25], v[150:153], v[182:185], v[22:25]
	v_mfma_f32_16x16x32_bf16 v[14:17], v[154:157], v[178:181], v[14:17]
	v_mfma_f32_16x16x32_bf16 v[14:17], v[158:161], v[182:185], v[14:17]
	s_setprio 3
	s_barrier
	v_mfma_f32_16x16x32_bf16 v[6:9], v[146:149], v[186:189], v[6:9]
	v_mfma_f32_16x16x32_bf16 v[6:9], v[150:153], v[190:193], v[6:9]
	v_mfma_f32_16x16x32_bf16 v[2:5], v[154:157], v[186:189], v[2:5]
	v_mfma_f32_16x16x32_bf16 v[2:5], v[158:161], v[190:193], v[2:5]
	s_setprio 0
	s_add_i32 s35, 0, 0x18000
	s_add_i32 s84, 0, 0x1c000
	v_add_u32_e32 v142, s35, v212
	v_add_u32_e32 v158, s84, v212
	ds_read_b128 v[130:133], v142
	ds_read_b128 v[134:137], v142 offset:1024
	ds_read_b128 v[138:141], v142 offset:2048
	ds_read_b128 v[142:145], v142 offset:3072
	ds_read_b128 v[146:149], v158
	ds_read_b128 v[150:153], v158 offset:1024
	ds_read_b128 v[154:157], v158 offset:2048
	ds_read_b128 v[158:161], v158 offset:3072
	s_add_u32 s68, s68, s2
	s_addc_u32 s69, s69, 0
	s_mov_b32 m0, s25
	v_lshl_add_u64 v[206:207], s[68:69], 0, v[0:1]
	ds_read_b128 v[162:165], v245 offset:32768
	ds_read_b128 v[166:169], v245 offset:33792
	ds_read_b128 v[170:173], v245 offset:34816
	ds_read_b128 v[174:177], v245 offset:35840
	ds_read_b128 v[178:181], v245 offset:36864
	ds_read_b128 v[182:185], v245 offset:37888
	ds_read_b128 v[186:189], v245 offset:38912
	ds_read_b128 v[190:193], v245 offset:39936
	global_load_lds_dwordx4 v[206:207], off
	v_lshl_add_u64 v[206:207], s[68:69], 0, v[222:223]
	s_mov_b32 m0, s36
	s_nop 0
	global_load_lds_dwordx4 v[206:207], off
	s_waitcnt vmcnt(8)
	s_waitcnt lgkmcnt(0)
	s_barrier
	s_setprio 1
	s_waitcnt lgkmcnt(0)
	v_mfma_f32_16x16x32_bf16 v[126:129], v[130:133], v[162:165], v[126:129]
	v_mfma_f32_16x16x32_bf16 v[126:129], v[134:137], v[166:169], v[126:129]
	v_mfma_f32_16x16x32_bf16 v[122:125], v[138:141], v[162:165], v[122:125]
	v_mfma_f32_16x16x32_bf16 v[122:125], v[142:145], v[166:169], v[122:125]
	v_mfma_f32_16x16x32_bf16 v[114:117], v[130:133], v[170:173], v[114:117]
	v_mfma_f32_16x16x32_bf16 v[114:117], v[134:137], v[174:177], v[114:117]
	v_mfma_f32_16x16x32_bf16 v[106:109], v[138:141], v[170:173], v[106:109]
	v_mfma_f32_16x16x32_bf16 v[106:109], v[142:145], v[174:177], v[106:109]
	v_mfma_f32_16x16x32_bf16 v[98:101], v[130:133], v[178:181], v[98:101]
	v_mfma_f32_16x16x32_bf16 v[98:101], v[134:137], v[182:185], v[98:101]
	v_mfma_f32_16x16x32_bf16 v[90:93], v[138:141], v[178:181], v[90:93]
	v_mfma_f32_16x16x32_bf16 v[90:93], v[142:145], v[182:185], v[90:93]
	v_mfma_f32_16x16x32_bf16 v[82:85], v[130:133], v[186:189], v[82:85]
	v_mfma_f32_16x16x32_bf16 v[82:85], v[134:137], v[190:193], v[82:85]
	v_mfma_f32_16x16x32_bf16 v[74:77], v[138:141], v[186:189], v[74:77]
	v_mfma_f32_16x16x32_bf16 v[74:77], v[142:145], v[190:193], v[74:77]
	s_setprio 0
	s_setprio 1
	v_mfma_f32_16x16x32_bf16 v[118:121], v[146:149], v[162:165], v[118:121]
	v_mfma_f32_16x16x32_bf16 v[118:121], v[150:153], v[166:169], v[118:121]
	v_mfma_f32_16x16x32_bf16 v[110:113], v[154:157], v[162:165], v[110:113]
	v_mfma_f32_16x16x32_bf16 v[110:113], v[158:161], v[166:169], v[110:113]
	v_mfma_f32_16x16x32_bf16 v[102:105], v[146:149], v[170:173], v[102:105]
	v_mfma_f32_16x16x32_bf16 v[102:105], v[150:153], v[174:177], v[102:105]
	v_mfma_f32_16x16x32_bf16 v[94:97], v[154:157], v[170:173], v[94:97]
	v_mfma_f32_16x16x32_bf16 v[94:97], v[158:161], v[174:177], v[94:97]
	v_mfma_f32_16x16x32_bf16 v[86:89], v[146:149], v[178:181], v[86:89]
	v_mfma_f32_16x16x32_bf16 v[86:89], v[150:153], v[182:185], v[86:89]
	v_mfma_f32_16x16x32_bf16 v[78:81], v[154:157], v[178:181], v[78:81]
	v_mfma_f32_16x16x32_bf16 v[78:81], v[158:161], v[182:185], v[78:81]
	s_setprio 3
	s_barrier
	v_mfma_f32_16x16x32_bf16 v[70:73], v[146:149], v[186:189], v[70:73]
	v_mfma_f32_16x16x32_bf16 v[70:73], v[150:153], v[190:193], v[70:73]
	v_mfma_f32_16x16x32_bf16 v[66:69], v[154:157], v[186:189], v[66:69]
	v_mfma_f32_16x16x32_bf16 v[66:69], v[158:161], v[190:193], v[66:69]
	s_setprio 0
	s_add_i32 s35, s35, s19
	v_lshl_add_u64 v[194:195], v[194:195], 0, s[22:23]
	s_mov_b32 m0, s35
	ds_read_b128 v[162:165], v245 offset:49152
	ds_read_b128 v[166:169], v245 offset:50176
	ds_read_b128 v[170:173], v245 offset:51200
	ds_read_b128 v[174:177], v245 offset:52224
	ds_read_b128 v[178:181], v245 offset:53248
	ds_read_b128 v[182:185], v245 offset:54272
	ds_read_b128 v[186:189], v245 offset:55296
	ds_read_b128 v[190:193], v245 offset:56320
	global_load_lds_dwordx4 v[194:195], off
	v_lshl_add_u64 v[194:195], v[196:197], 0, s[22:23]
	s_add_i32 m0, s35, 0x2000
	s_add_i32 s35, s84, s19
	global_load_lds_dwordx4 v[194:195], off
	v_lshl_add_u64 v[194:195], v[198:199], 0, s[22:23]
	s_mov_b32 m0, s35
	s_nop 0
	global_load_lds_dwordx4 v[194:195], off
	v_lshl_add_u64 v[194:195], v[200:201], 0, s[22:23]
	s_add_i32 m0, s35, 0x2000
	s_nop 0
	global_load_lds_dwordx4 v[194:195], off
	v_lshl_add_u64 v[194:195], v[202:203], 0, s[22:23]
	s_mov_b32 m0, s37
	s_nop 0
	global_load_lds_dwordx4 v[194:195], off
	v_lshl_add_u64 v[194:195], v[204:205], 0, s[22:23]
	s_mov_b32 m0, s40
	s_nop 0
	global_load_lds_dwordx4 v[194:195], off
	s_waitcnt vmcnt(8)
	s_waitcnt lgkmcnt(0)
	s_barrier
	s_setprio 1
	s_waitcnt lgkmcnt(0)
	v_mfma_f32_16x16x32_bf16 v[62:65], v[130:133], v[162:165], v[62:65]
	v_mfma_f32_16x16x32_bf16 v[62:65], v[134:137], v[166:169], v[62:65]
	v_mfma_f32_16x16x32_bf16 v[58:61], v[138:141], v[162:165], v[58:61]
	v_mfma_f32_16x16x32_bf16 v[58:61], v[142:145], v[166:169], v[58:61]
	v_mfma_f32_16x16x32_bf16 v[50:53], v[130:133], v[170:173], v[50:53]
	v_mfma_f32_16x16x32_bf16 v[50:53], v[134:137], v[174:177], v[50:53]
	v_mfma_f32_16x16x32_bf16 v[42:45], v[138:141], v[170:173], v[42:45]
	v_mfma_f32_16x16x32_bf16 v[42:45], v[142:145], v[174:177], v[42:45]
	v_mfma_f32_16x16x32_bf16 v[34:37], v[130:133], v[178:181], v[34:37]
	v_mfma_f32_16x16x32_bf16 v[34:37], v[134:137], v[182:185], v[34:37]
	v_mfma_f32_16x16x32_bf16 v[26:29], v[138:141], v[178:181], v[26:29]
	v_mfma_f32_16x16x32_bf16 v[26:29], v[142:145], v[182:185], v[26:29]
	v_mfma_f32_16x16x32_bf16 v[18:21], v[130:133], v[186:189], v[18:21]
	v_mfma_f32_16x16x32_bf16 v[18:21], v[134:137], v[190:193], v[18:21]
	v_mfma_f32_16x16x32_bf16 v[10:13], v[138:141], v[186:189], v[10:13]
	v_mfma_f32_16x16x32_bf16 v[10:13], v[142:145], v[190:193], v[10:13]
	s_setprio 0
	s_setprio 1
	v_mfma_f32_16x16x32_bf16 v[54:57], v[146:149], v[162:165], v[54:57]
	v_mfma_f32_16x16x32_bf16 v[54:57], v[150:153], v[166:169], v[54:57]
	v_mfma_f32_16x16x32_bf16 v[46:49], v[154:157], v[162:165], v[46:49]
	v_mfma_f32_16x16x32_bf16 v[46:49], v[158:161], v[166:169], v[46:49]
	v_mfma_f32_16x16x32_bf16 v[38:41], v[146:149], v[170:173], v[38:41]
	v_mfma_f32_16x16x32_bf16 v[38:41], v[150:153], v[174:177], v[38:41]
	v_mfma_f32_16x16x32_bf16 v[30:33], v[154:157], v[170:173], v[30:33]
	v_mfma_f32_16x16x32_bf16 v[30:33], v[158:161], v[174:177], v[30:33]
	v_mfma_f32_16x16x32_bf16 v[22:25], v[146:149], v[178:181], v[22:25]
	v_mfma_f32_16x16x32_bf16 v[22:25], v[150:153], v[182:185], v[22:25]
	v_mfma_f32_16x16x32_bf16 v[14:17], v[154:157], v[178:181], v[14:17]
	v_mfma_f32_16x16x32_bf16 v[14:17], v[158:161], v[182:185], v[14:17]
	s_setprio 3
	s_barrier
	v_mfma_f32_16x16x32_bf16 v[6:9], v[146:149], v[186:189], v[6:9]
	v_mfma_f32_16x16x32_bf16 v[6:9], v[150:153], v[190:193], v[6:9]
	v_mfma_f32_16x16x32_bf16 v[2:5], v[154:157], v[186:189], v[2:5]
	v_mfma_f32_16x16x32_bf16 v[2:5], v[158:161], v[190:193], v[2:5]
	s_setprio 0
	s_add_u32 s0, s0, 0x100
	s_addc_u32 s1, s1, 0
	s_add_u32 vcc_lo, vcc_lo, 0x100
	s_addc_u32 vcc_hi, vcc_hi, 0
	s_cmp_ge_u32 s34, s18
	s_mov_b32 s68, s34
	s_cbranch_scc0 .LBB0_707
	s_and_b64 vcc, exec, s[50:51]
	s_cbranch_vccz .LBB0_710
	s_barrier
